# pass A prefetch: unit-top wait relaxed to vmcnt(10) so previous unit's stores are not waited
# speedup vs baseline: 1.0267x; 1.0022x over previous
.LBB0_199:
	s_bitcmp0_b32 s64, 0
	s_cselect_b64 s[94:95], -1, 0
	s_cmp_lt_i32 s20, 1
	s_cselect_b64 s[2:3], -1, 0
	s_or_b64 s[2:3], s[94:95], s[2:3]
	s_mov_b32 s1, 0
	s_and_b64 vcc, exec, s[2:3]
	s_cbranch_vccnz .LBB0_222
	s_cmp_lt_i32 s64, 64
	s_cselect_b32 s0, 64, 0xffffffc0
	s_add_i32 s8, s64, s0
	s_addk_i32 s8, 0x700
	s_add_u32 s34, s90, 0x1e800000
	s_addc_u32 s35, s91, 0
	v_readlane_b32 s2, v246, 36
	s_add_u32 s56, s90, 0x1ea00000
	v_readlane_b32 s3, v246, 37
	s_addc_u32 s57, s91, 0
	s_movk_i32 s9, 0x2880
	v_mov_b64_e32 v[32:33], s[2:3]
	s_movk_i32 s10, 0x1000
	s_mov_b32 s11, 0x800000
	s_mov_b32 s16, 0x3f317217
	s_mov_b32 s17, 0x7f800000
	v_mov_b32_e32 v46, 0x41b17218
	s_movk_i32 s18, 0x7f
	s_movk_i32 s19, 0x2040
	s_add_i32 s21, 0, 0x8100
	s_movk_i32 s22, 0x480
	s_movk_i32 s23, 0x48
	v_mov_b32_e32 v35, 0
	s_movk_i32 s24, 0x90
	s_mov_b32 s25, 0
	s_mov_b32 s99, s64
	s_lshl_b32 s100, s99, 3
	s_lshl_b32 s101, s99, 6
	s_and_b32 s100, s100, 0xffffe000
	s_and_b32 s101, s101, 0x1fc0
	s_or_b32 s100, s100, s101
	s_and_b32 s98, s99, 0x380
	v_ashrrev_i32_e32 v206, 6, v210
	v_bfi_b32 v208, -4, v206, v210
	v_lshlrev_b32_e32 v208, 4, v208
	v_mov_b32_e32 v209, 0
	v_bfe_u32 v206, v210, 2, 6
	v_or_b32_e32 v206, s100, v206
	v_mad_i64_i32 v[200:201], vcc, v206, s9, v[32:33]
	s_lshl_b32 s100, s98, 1
	s_mov_b32 s101, 0
	v_lshl_add_u64 v[200:201], v[200:201], 0, s[100:101]
	v_lshl_add_u64 v[200:201], v[208:209], 1, v[200:201]
	v_add_u32_e32 v202, s98, v208
	v_mov_b32_e32 v203, 0
	v_lshl_add_u64 v[202:203], v[202:203], 2, s[54:55]
	s_movk_i32 s100, 0x1000
	v_lshl_add_u64 v[204:205], v[200:201], 0, s[100:101]
	global_load_dwordx4 v[160:163], v[200:201], off offset:2048
	global_load_dwordx4 v[164:167], v[200:201], off offset:2064
	global_load_dwordx4 v[168:171], v[202:203], off
	global_load_dwordx4 v[172:175], v[202:203], off offset:16
	global_load_dwordx4 v[176:179], v[200:201], off offset:16
	global_load_dwordx4 v[180:183], v[200:201], off
	global_load_dwordx4 v[184:187], v[204:205], off
	global_load_dwordx4 v[188:191], v[204:205], off offset:16
	global_load_dwordx4 v[192:195], v[202:203], off offset:48
	global_load_dwordx4 v[196:199], v[202:203], off offset:32
	s_waitcnt vmcnt(0)
	s_branch .LBB0_202

.LBB0_208:
	s_lshl_b32 s0, s58, 3
	s_lshl_b32 s2, s58, 6
	v_mov_b32_e32 v36, v210
	s_and_b32 s0, s0, 0xffffe000
	s_and_b32 s2, s2, 0x1fc0
	s_or_b32 s27, s0, s2
	v_ashrrev_i32_e32 v0, 6, v36
	v_bfe_u32 v37, v36, 2, 6
	s_and_b32 s4, s58, 0x380
	v_bfi_b32 v34, -4, v0, v36
	v_or_b32_e32 v0, s27, v37
	v_lshlrev_b32_e32 v24, 4, v34
	v_mad_i64_i32 v[0:1], s[2:3], v0, s9, v[32:33]
	s_lshl_b32 s0, s4, 1
	v_lshl_add_u64 v[0:1], v[0:1], 0, s[0:1]
	v_ashrrev_i32_e32 v25, 31, v24
	v_lshl_add_u64 v[0:1], v[24:25], 1, v[0:1]
	s_waitcnt vmcnt(10)
	v_mov_b32_e32 v26, v160
	v_mov_b32_e32 v27, v161
	v_mov_b32_e32 v28, v162
	v_mov_b32_e32 v29, v163
	v_mov_b32_e32 v38, v164
	v_mov_b32_e32 v39, v165
	v_mov_b32_e32 v40, v166
	v_mov_b32_e32 v41, v167
	v_add_u32_e32 v2, s4, v24
	v_ashrrev_i32_e32 v3, 31, v2
	v_lshl_add_u64 v[20:21], v[2:3], 2, s[54:55]
	v_mov_b32_e32 v42, v168
	v_mov_b32_e32 v43, v169
	v_mov_b32_e32 v44, v170
	v_mov_b32_e32 v45, v171
	v_mov_b32_e32 v48, v172
	v_mov_b32_e32 v49, v173
	v_mov_b32_e32 v50, v174
	v_mov_b32_e32 v51, v175
	v_mul_u32_u24_e32 v2, 0x204, v37
	v_lshlrev_b32_e32 v3, 6, v34
	v_add3_u32 v47, 0, v2, v3
	v_add_co_u32_e32 v2, vcc, s10, v0
	v_readfirstlane_b32 s26, v36
	s_nop 0
	v_addc_co_u32_e32 v3, vcc, 0, v1, vcc
	v_mov_b32_e32 v4, v176
	v_mov_b32_e32 v5, v177
	v_mov_b32_e32 v6, v178
	v_mov_b32_e32 v7, v179
	v_mov_b32_e32 v12, v180
	v_mov_b32_e32 v13, v181
	v_mov_b32_e32 v14, v182
	v_mov_b32_e32 v15, v183
	v_mov_b32_e32 v8, v184
	v_mov_b32_e32 v9, v185
	v_mov_b32_e32 v10, v186
	v_mov_b32_e32 v11, v187
	s_nop 0
	v_mov_b32_e32 v0, v188
	v_mov_b32_e32 v1, v189
	v_mov_b32_e32 v2, v190
	v_mov_b32_e32 v3, v191
	s_nop 0
	v_mov_b32_e32 v16, v192
	v_mov_b32_e32 v17, v193
	v_mov_b32_e32 v18, v194
	v_mov_b32_e32 v19, v195
	s_nop 0
	v_mov_b32_e32 v20, v196
	v_mov_b32_e32 v21, v197
	v_mov_b32_e32 v22, v198
	v_mov_b32_e32 v23, v199
	s_add_i32 s98, s25, 1
	s_cmp_ge_u32 s98, s20
	s_cbranch_scc1 .Lpa1_nopf
	s_lshl_b32 s99, s98, 8
	s_add_i32 s99, s99, s64
	s_cmp_gt_u32 s98, 7
	s_cselect_b32 s99, s8, s99
	s_lshl_b32 s100, s99, 3
	s_lshl_b32 s101, s99, 6
	s_and_b32 s100, s100, 0xffffe000
	s_and_b32 s101, s101, 0x1fc0
	s_or_b32 s100, s100, s101
	s_and_b32 s98, s99, 0x380
	v_ashrrev_i32_e32 v206, 6, v210
	v_bfi_b32 v208, -4, v206, v210
	v_lshlrev_b32_e32 v208, 4, v208
	v_mov_b32_e32 v209, 0
	v_bfe_u32 v206, v210, 2, 6
	v_or_b32_e32 v206, s100, v206
	v_mad_i64_i32 v[200:201], vcc, v206, s9, v[32:33]
	s_lshl_b32 s100, s98, 1
	s_mov_b32 s101, 0
	v_lshl_add_u64 v[200:201], v[200:201], 0, s[100:101]
	v_lshl_add_u64 v[200:201], v[208:209], 1, v[200:201]
	v_add_u32_e32 v202, s98, v208
	v_mov_b32_e32 v203, 0
	v_lshl_add_u64 v[202:203], v[202:203], 2, s[54:55]
	s_movk_i32 s100, 0x1000
	v_lshl_add_u64 v[204:205], v[200:201], 0, s[100:101]
	global_load_dwordx4 v[160:163], v[200:201], off offset:2048
	global_load_dwordx4 v[164:167], v[200:201], off offset:2064
	global_load_dwordx4 v[168:171], v[202:203], off
	global_load_dwordx4 v[172:175], v[202:203], off offset:16
	global_load_dwordx4 v[176:179], v[200:201], off offset:16
	global_load_dwordx4 v[180:183], v[200:201], off
	global_load_dwordx4 v[184:187], v[204:205], off
	global_load_dwordx4 v[188:191], v[204:205], off offset:16
	global_load_dwordx4 v[192:195], v[202:203], off offset:48
	global_load_dwordx4 v[196:199], v[202:203], off offset:32

.LBB0_394:
	s_cmp_gt_i32 s20, 0
	s_cselect_b64 s[2:3], -1, 0
	s_and_b64 s[2:3], s[94:95], s[2:3]
	s_andn2_b64 vcc, exec, s[2:3]
	s_mov_b32 s15, 0
	s_cbranch_vccnz .LBB0_417
	s_add_i32 s2, s64, 64
	s_and_b64 s[0:1], s[0:1], exec
	s_cselect_b32 s8, s2, s10
	s_addk_i32 s8, 0x700
	s_add_u32 s0, s90, 0x1e800000
	s_addc_u32 s1, s91, 0
	v_readlane_b32 s2, v246, 36
	s_add_u32 s34, s90, 0x1ea00000
	v_readlane_b32 s3, v246, 37
	s_addc_u32 s35, s91, 0
	s_movk_i32 s9, 0x2880
	v_mov_b64_e32 v[32:33], s[2:3]
	s_movk_i32 s10, 0x1000
	s_mov_b32 s11, 0x800000
	s_mov_b32 s16, 0x3f317217
	s_mov_b32 s17, 0x7f800000
	v_mov_b32_e32 v46, 0x41b17218
	s_movk_i32 s18, 0x7f
	s_movk_i32 s19, 0x2040
	s_add_i32 s21, 0, 0x8100
	s_movk_i32 s22, 0x480
	s_movk_i32 s23, 0x48
	v_mov_b32_e32 v35, 0
	s_movk_i32 s24, 0x90
	s_mov_b32 s25, 0
	s_mov_b32 s99, s64
	s_lshl_b32 s100, s99, 3
	s_lshl_b32 s101, s99, 6
	s_and_b32 s100, s100, 0xffffe000
	s_and_b32 s101, s101, 0x1fc0
	s_or_b32 s100, s100, s101
	s_and_b32 s98, s99, 0x380
	v_ashrrev_i32_e32 v206, 6, v210
	v_bfi_b32 v208, -4, v206, v210
	v_lshlrev_b32_e32 v208, 4, v208
	v_mov_b32_e32 v209, 0
	v_bfe_u32 v206, v210, 2, 6
	v_or_b32_e32 v206, s100, v206
	v_mad_i64_i32 v[200:201], vcc, v206, s9, v[32:33]
	s_lshl_b32 s100, s98, 1
	s_mov_b32 s101, 0
	v_lshl_add_u64 v[200:201], v[200:201], 0, s[100:101]
	v_lshl_add_u64 v[200:201], v[208:209], 1, v[200:201]
	v_add_u32_e32 v202, s98, v208
	v_mov_b32_e32 v203, 0
	v_lshl_add_u64 v[202:203], v[202:203], 2, s[54:55]
	s_movk_i32 s100, 0x1000
	v_lshl_add_u64 v[204:205], v[200:201], 0, s[100:101]
	global_load_dwordx4 v[160:163], v[200:201], off offset:2048
	global_load_dwordx4 v[164:167], v[200:201], off offset:2064
	global_load_dwordx4 v[168:171], v[202:203], off
	global_load_dwordx4 v[172:175], v[202:203], off offset:16
	global_load_dwordx4 v[176:179], v[200:201], off offset:16
	global_load_dwordx4 v[180:183], v[200:201], off
	global_load_dwordx4 v[184:187], v[204:205], off
	global_load_dwordx4 v[188:191], v[204:205], off offset:16
	global_load_dwordx4 v[192:195], v[202:203], off offset:48
	global_load_dwordx4 v[196:199], v[202:203], off offset:32
	s_waitcnt vmcnt(0)
	s_branch .LBB0_397

.LBB0_403:
	s_lshl_b32 s2, s56, 3
	s_lshl_b32 s3, s56, 6
	v_mov_b32_e32 v36, v210
	s_and_b32 s2, s2, 0xffffe000
	s_and_b32 s3, s3, 0x1fc0
	s_or_b32 s27, s2, s3
	v_ashrrev_i32_e32 v0, 6, v36
	v_bfe_u32 v37, v36, 2, 6
	s_and_b32 s4, s56, 0x380
	v_bfi_b32 v34, -4, v0, v36
	v_or_b32_e32 v0, s27, v37
	v_lshlrev_b32_e32 v24, 4, v34
	v_mad_i64_i32 v[0:1], s[2:3], v0, s9, v[32:33]
	s_lshl_b32 s14, s4, 1
	v_lshl_add_u64 v[0:1], v[0:1], 0, s[14:15]
	v_ashrrev_i32_e32 v25, 31, v24
	v_lshl_add_u64 v[0:1], v[24:25], 1, v[0:1]
	s_waitcnt vmcnt(10)
	v_mov_b32_e32 v26, v160
	v_mov_b32_e32 v27, v161
	v_mov_b32_e32 v28, v162
	v_mov_b32_e32 v29, v163
	v_mov_b32_e32 v38, v164
	v_mov_b32_e32 v39, v165
	v_mov_b32_e32 v40, v166
	v_mov_b32_e32 v41, v167
	v_add_u32_e32 v2, s4, v24
	v_ashrrev_i32_e32 v3, 31, v2
	v_lshl_add_u64 v[20:21], v[2:3], 2, s[54:55]
	v_mov_b32_e32 v42, v168
	v_mov_b32_e32 v43, v169
	v_mov_b32_e32 v44, v170
	v_mov_b32_e32 v45, v171
	v_mov_b32_e32 v48, v172
	v_mov_b32_e32 v49, v173
	v_mov_b32_e32 v50, v174
	v_mov_b32_e32 v51, v175
	v_mul_u32_u24_e32 v2, 0x204, v37
	v_lshlrev_b32_e32 v3, 6, v34
	v_add3_u32 v47, 0, v2, v3
	v_add_co_u32_e32 v2, vcc, s10, v0
	v_readfirstlane_b32 s26, v36
	s_nop 0
	v_addc_co_u32_e32 v3, vcc, 0, v1, vcc
	v_mov_b32_e32 v4, v176
	v_mov_b32_e32 v5, v177
	v_mov_b32_e32 v6, v178
	v_mov_b32_e32 v7, v179
	v_mov_b32_e32 v12, v180
	v_mov_b32_e32 v13, v181
	v_mov_b32_e32 v14, v182
	v_mov_b32_e32 v15, v183
	v_mov_b32_e32 v8, v184
	v_mov_b32_e32 v9, v185
	v_mov_b32_e32 v10, v186
	v_mov_b32_e32 v11, v187
	s_nop 0
	v_mov_b32_e32 v0, v188
	v_mov_b32_e32 v1, v189
	v_mov_b32_e32 v2, v190
	v_mov_b32_e32 v3, v191
	s_nop 0
	v_mov_b32_e32 v16, v192
	v_mov_b32_e32 v17, v193
	v_mov_b32_e32 v18, v194
	v_mov_b32_e32 v19, v195
	s_nop 0
	v_mov_b32_e32 v20, v196
	v_mov_b32_e32 v21, v197
	v_mov_b32_e32 v22, v198
	v_mov_b32_e32 v23, v199
	s_add_i32 s98, s25, 1
	s_cmp_ge_u32 s98, s20
	s_cbranch_scc1 .Lpa2_nopf
	s_lshl_b32 s99, s98, 8
	s_add_i32 s99, s99, s64
	s_cmp_gt_u32 s98, 7
	s_cselect_b32 s99, s8, s99
	s_lshl_b32 s100, s99, 3
	s_lshl_b32 s101, s99, 6
	s_and_b32 s100, s100, 0xffffe000
	s_and_b32 s101, s101, 0x1fc0
	s_or_b32 s100, s100, s101
	s_and_b32 s98, s99, 0x380
	v_ashrrev_i32_e32 v206, 6, v210
	v_bfi_b32 v208, -4, v206, v210
	v_lshlrev_b32_e32 v208, 4, v208
	v_mov_b32_e32 v209, 0
	v_bfe_u32 v206, v210, 2, 6
	v_or_b32_e32 v206, s100, v206
	v_mad_i64_i32 v[200:201], vcc, v206, s9, v[32:33]
	s_lshl_b32 s100, s98, 1
	s_mov_b32 s101, 0
	v_lshl_add_u64 v[200:201], v[200:201], 0, s[100:101]
	v_lshl_add_u64 v[200:201], v[208:209], 1, v[200:201]
	v_add_u32_e32 v202, s98, v208
	v_mov_b32_e32 v203, 0
	v_lshl_add_u64 v[202:203], v[202:203], 2, s[54:55]
	s_movk_i32 s100, 0x1000
	v_lshl_add_u64 v[204:205], v[200:201], 0, s[100:101]
	global_load_dwordx4 v[160:163], v[200:201], off offset:2048
	global_load_dwordx4 v[164:167], v[200:201], off offset:2064
	global_load_dwordx4 v[168:171], v[202:203], off
	global_load_dwordx4 v[172:175], v[202:203], off offset:16
	global_load_dwordx4 v[176:179], v[200:201], off offset:16
	global_load_dwordx4 v[180:183], v[200:201], off
	global_load_dwordx4 v[184:187], v[204:205], off
	global_load_dwordx4 v[188:191], v[204:205], off offset:16
	global_load_dwordx4 v[192:195], v[202:203], off offset:48
	global_load_dwordx4 v[196:199], v[202:203], off offset:32
